# v89: mLSTM state pass, latent chunk loop: gate values of the next chunk fetched one chunk ahead (copied at chunk start), counted waits adjusted
# speedup vs baseline: 1.0138x; 1.0015x over previous
.LBB0_284:
	s_lshl_b32 s3, s52, 11
	s_addk_i32 s3, 0x2000
	s_lshl_b32 s44, s52, 8
	s_and_b64 s[42:43], s[40:41], exec
	s_cselect_b32 s62, 15, 2
	s_cselect_b32 s80, 16, 2
	s_cselect_b32 s44, s3, s44
	s_cmp_lg_u32 s78, 0
	s_cselect_b64 s[48:49], -1, 0
	s_lshl_b32 s53, s77, 8
	s_or_b32 s3, s53, s76
	s_add_i32 s81, s80, -1
	s_mulk_i32 s3, 0x6000
	s_add_u32 s3, s54, s3
	s_addc_u32 s50, s55, 0
	s_ashr_i32 s45, s44, 31
	s_lshl_b64 s[42:43], s[44:45], 1
	s_add_u32 s45, s3, s42
	s_addc_u32 s84, s50, s43
	s_lshl_b32 s3, s81, 7
	s_cmp_eq_u32 s78, 0
	s_cselect_b64 s[50:51], -1, 0
	s_and_b64 s[42:43], s[50:51], exec
	s_cselect_b32 s3, 0, s3
	v_mov_b32_e32 v8, v124
	s_lshl_b32 s3, s3, 1
	s_add_u32 s42, s45, s3
	v_lshlrev_b32_e32 v0, 4, v8
	s_addc_u32 s43, s84, 0
	v_and_b32_e32 v0, 0xf0, v0
	v_lshl_add_u64 v[2:3], s[42:43], 0, v[0:1]
	v_ashrrev_i32_e32 v0, 4, v8
	s_movk_i32 s3, 0x6000
	v_mad_i64_i32 v[4:5], s[42:43], v0, s3, v[2:3]
	v_add_u32_e32 v0, 0x200, v8
	v_ashrrev_i32_e32 v0, 4, v0
	v_mad_i64_i32 v[6:7], s[42:43], v0, s3, v[2:3]
	v_add_u32_e32 v0, 0x400, v8
	v_ashrrev_i32_e32 v0, 4, v0
	global_load_dwordx4 v[18:21], v[4:5], off
	global_load_dwordx4 v[22:25], v[6:7], off
	v_mad_i64_i32 v[4:5], s[42:43], v0, s3, v[2:3]
	v_add_u32_e32 v0, 0x600, v8
	v_ashrrev_i32_e32 v0, 4, v0
	v_mad_i64_i32 v[2:3], s[42:43], v0, s3, v[2:3]
	global_load_dwordx4 v[34:37], v[4:5], off
	global_load_dwordx4 v[38:41], v[2:3], off
	s_lshl_b32 s3, s77, 1
	s_add_i32 s3, s79, s3
	s_add_i32 s85, s3, s78
	s_addk_i32 s85, 0x100
	s_lshl_b32 s3, s37, 16
	s_add_u32 s56, s69, s3
	s_addc_u32 s57, s70, 0
	s_ashr_i32 s3, s2, 31
	s_lshl_b64 s[42:43], s[2:3], 1
	s_add_u32 s3, s56, s42
	s_addc_u32 s92, s57, s43
	s_cmp_eq_u32 s37, 0
	s_cselect_b64 s[42:43], -1, 0
	s_and_b64 s[56:57], s[6:7], s[42:43]
	s_and_b32 s36, s36, 3
	s_cmp_lg_u32 s36, 0
	s_cselect_b64 s[36:37], -1, 0
	s_lshl_b32 s58, s78, 5
	s_add_u32 s58, s0, s58
	s_addc_u32 s59, s1, 0
	s_lshl_b32 s60, s77, 2
	s_add_u32 s58, s58, s60
	s_addc_u32 s59, s59, 0
	s_add_i32 s53, s2, s53
	s_mul_hi_i32 s60, s53, 0x6000
	s_mulk_i32 s53, 0x6000
	v_cndmask_b32_e64 v0, 0, 1, s[36:37]
	v_readlane_b32 s36, v254, 63
	s_add_u32 s93, s46, s53
	s_addc_u32 s94, s47, s60
	v_or_b32_e32 v150, s36, v0
	s_lshl_b32 s52, s52, 7
	s_lshl_b32 s53, s77, 5
	v_or_b32_e32 v106, s2, v125
	v_or_b32_e32 v0, v150, v125
	s_or_b32 s52, s52, s53
	s_lshl_b32 s53, s78, 4
	s_mov_b32 s97, 0
	v_ashrrev_i32_e32 v107, 31, v106
	v_cmp_eq_u32_e64 s[36:37], 0, v0
	s_or_b32 s95, s52, s53
	global_load_dword v176, v1, s[58:59]
	global_load_dword v176, v1, s[58:59]
	global_load_dword v176, v1, s[58:59]
	global_load_dword v176, v1, s[58:59]
	s_branch .LBB0_287
.LBB0_285:
	v_sub_f32_e32 v51, s61, v54
	s_waitcnt vmcnt(12)
	v_add_f32_e32 v50, v50, v51
	v_sub_f32_e32 v51, s61, v55
	v_add_f32_e32 v0, v0, v51
	v_max_f32_e32 v51, v50, v0
	ds_bpermute_b32 v52, v141, v51
	v_add_f32_e32 v53, s61, v151
	s_ashr_i32 s61, s60, 31
	s_lshl_b64 s[52:53], s[60:61], 1
	s_add_u32 s60, s93, s52
	s_waitcnt lgkmcnt(0)
	v_max_f32_e32 v52, v52, v52
	v_max_f32_e32 v51, v51, v52
	ds_bpermute_b32 v52, v142, v51
	s_addc_u32 s61, s94, s53
	s_waitcnt lgkmcnt(0)
	v_max_f32_e32 v52, v52, v52
	v_max_f32_e32 v51, v51, v52
	ds_bpermute_b32 v52, v143, v51
	s_waitcnt lgkmcnt(0)
	v_max_f32_e32 v52, v52, v52
	v_max_f32_e32 v51, v51, v52
	ds_bpermute_b32 v52, v144, v51
	s_waitcnt lgkmcnt(0)
	v_max_f32_e32 v52, v52, v52
	v_max_f32_e32 v51, v51, v52
	ds_bpermute_b32 v52, v145, v51
	s_waitcnt lgkmcnt(0)
	v_max_f32_e32 v52, v52, v52
	v_max_f32_e32 v51, v51, v52
	ds_bpermute_b32 v52, v146, v51
	s_waitcnt lgkmcnt(0)
	v_max3_f32 v153, v53, v51, v52
	v_sub_f32_e32 v50, v50, v153
	v_sub_f32_e32 v0, v0, v153
	v_mul_f32_e32 v50, 0x3fb8aa3b, v50
	v_mul_f32_e32 v0, 0x3fb8aa3b, v0
	v_exp_f32_e32 v50, v50
	v_exp_f32_e32 v51, v0
	v_sub_f32_e32 v0, v53, v153
	v_mul_f32_e32 v0, 0x3fb8aa3b, v0
	v_exp_f32_e32 v0, v0
	ds_write_b64 v147, v[50:51]
	ds_read_b128 v[82:85], v148
	ds_read_b128 v[86:89], v148 offset:16
	s_waitcnt vmcnt(11)
	v_mov_b32_e32 v90, v180
	v_mov_b32_e32 v91, v181
	v_mov_b32_e32 v92, v182
	v_mov_b32_e32 v93, v183
	v_pk_mul_f32 v[80:81], v[48:49], v[0:1] op_sel_hi:[1,0]
	v_pk_mul_f32 v[78:79], v[46:47], v[0:1] op_sel_hi:[1,0]
	v_pk_mul_f32 v[76:77], v[44:45], v[0:1] op_sel_hi:[1,0]
	v_pk_mul_f32 v[74:75], v[42:43], v[0:1] op_sel_hi:[1,0]
	v_pk_mul_f32 v[72:73], v[32:33], v[0:1] op_sel_hi:[1,0]
	v_pk_mul_f32 v[70:71], v[30:31], v[0:1] op_sel_hi:[1,0]
	v_pk_mul_f32 v[68:69], v[28:29], v[0:1] op_sel_hi:[1,0]
	v_pk_mul_f32 v[66:67], v[26:27], v[0:1] op_sel_hi:[1,0]
	v_pk_mul_f32 v[64:65], v[16:17], v[0:1] op_sel_hi:[1,0]
	v_pk_mul_f32 v[62:63], v[14:15], v[0:1] op_sel_hi:[1,0]
	v_pk_mul_f32 v[60:61], v[12:13], v[0:1] op_sel_hi:[1,0]
	v_pk_mul_f32 v[58:59], v[10:11], v[0:1] op_sel_hi:[1,0]
	v_pk_mul_f32 v[56:57], v[8:9], v[0:1] op_sel_hi:[1,0]
	v_pk_mul_f32 v[54:55], v[6:7], v[0:1] op_sel_hi:[1,0]
	v_pk_mul_f32 v[52:53], v[4:5], v[0:1] op_sel_hi:[1,0]
	v_pk_mul_f32 v[50:51], v[2:3], v[0:1] op_sel_hi:[1,0]
	s_waitcnt vmcnt(8)
	v_lshlrev_b32_e32 v94, 16, v90
	v_and_b32_e32 v95, 0xffff0000, v90
	v_lshlrev_b32_e32 v90, 16, v91
	v_and_b32_e32 v91, 0xffff0000, v91
	s_waitcnt lgkmcnt(1)
	v_pk_mul_f32 v[84:85], v[84:85], v[90:91]
	v_lshlrev_b32_e32 v90, 16, v92
	v_and_b32_e32 v91, 0xffff0000, v92
	v_pk_mul_f32 v[82:83], v[82:83], v[94:95]
	s_waitcnt lgkmcnt(0)
	v_pk_mul_f32 v[86:87], v[86:87], v[90:91]
	v_lshlrev_b32_e32 v90, 16, v93
	v_and_b32_e32 v91, 0xffff0000, v93
	v_pk_mul_f32 v[88:89], v[88:89], v[90:91]
	v_mov_b32_e32 v90, v82
	v_mov_b32_e32 v91, v86
	v_mov_b32_e32 v92, v83
	v_mov_b32_e32 v93, v87
	v_pk_add_f32 v[90:91], v[90:91], v[92:93]
	v_mov_b32_e32 v92, v84
	v_mov_b32_e32 v93, v88
	v_mov_b32_e32 v94, v85
	v_mov_b32_e32 v95, v89
	v_pk_add_f32 v[92:93], v[92:93], v[94:95]
	v_cvt_pk_bf16_f32 v82, v82, v83
	v_pk_add_f32 v[90:91], v[90:91], v[92:93]
	v_cvt_pk_bf16_f32 v83, v84, v85
	v_pk_add_f32 v[108:109], v[90:91], v[90:91] op_sel:[0,1] op_sel_hi:[1,0]
	v_cvt_pk_bf16_f32 v84, v86, v87
	v_cvt_pk_bf16_f32 v85, v88, v89
	ds_read_b128 v[86:89], v148 offset:128
	ds_read_b128 v[90:93], v148 offset:144
	s_waitcnt vmcnt(10)
	v_mov_b32_e32 v94, v184
	v_mov_b32_e32 v95, v185
	v_mov_b32_e32 v96, v186
	v_mov_b32_e32 v97, v187
	s_waitcnt vmcnt(8)
	v_lshlrev_b32_e32 v98, 16, v94
	v_and_b32_e32 v99, 0xffff0000, v94
	v_lshlrev_b32_e32 v94, 16, v95
	v_and_b32_e32 v95, 0xffff0000, v95
	s_waitcnt lgkmcnt(1)
	v_pk_mul_f32 v[88:89], v[88:89], v[94:95]
	v_lshlrev_b32_e32 v94, 16, v96
	v_and_b32_e32 v95, 0xffff0000, v96
	v_pk_mul_f32 v[86:87], v[86:87], v[98:99]
	s_waitcnt lgkmcnt(0)
	v_pk_mul_f32 v[90:91], v[90:91], v[94:95]
	v_lshlrev_b32_e32 v94, 16, v97
	v_and_b32_e32 v95, 0xffff0000, v97
	v_pk_mul_f32 v[92:93], v[92:93], v[94:95]
	v_mov_b32_e32 v94, v86
	v_mov_b32_e32 v95, v88
	v_mov_b32_e32 v96, v87
	v_mov_b32_e32 v97, v89
	v_pk_add_f32 v[94:95], v[94:95], v[96:97]
	v_mov_b32_e32 v96, v91
	v_pk_add_f32 v[110:111], v[94:95], v[94:95] op_sel:[0,1] op_sel_hi:[1,0]
	v_mov_b32_e32 v94, v90
	v_mov_b32_e32 v95, v92
	v_mov_b32_e32 v97, v93
	v_pk_add_f32 v[94:95], v[94:95], v[96:97]
	v_cvt_pk_bf16_f32 v86, v86, v87
	v_pk_add_f32 v[112:113], v[94:95], v[94:95] op_sel:[0,1] op_sel_hi:[1,0]
	v_cvt_pk_bf16_f32 v87, v88, v89
	v_cvt_pk_bf16_f32 v88, v90, v91
	v_cvt_pk_bf16_f32 v89, v92, v93
	ds_read_b128 v[94:97], v148 offset:256
	ds_read_b128 v[90:93], v148 offset:272
	s_waitcnt vmcnt(9)
	v_mov_b32_e32 v98, v188
	v_mov_b32_e32 v99, v189
	v_mov_b32_e32 v100, v190
	v_mov_b32_e32 v101, v191
	s_waitcnt vmcnt(8)
	v_lshlrev_b32_e32 v104, 16, v98
	v_and_b32_e32 v105, 0xffff0000, v98
	v_lshlrev_b32_e32 v98, 16, v99
	v_and_b32_e32 v99, 0xffff0000, v99
	v_lshlrev_b32_e32 v114, 16, v100
	v_and_b32_e32 v115, 0xffff0000, v100
	v_lshlrev_b32_e32 v100, 16, v101
	v_and_b32_e32 v101, 0xffff0000, v101
	s_waitcnt lgkmcnt(1)
	v_pk_mul_f32 v[122:123], v[94:95], v[104:105]
	v_pk_mul_f32 v[154:155], v[96:97], v[98:99]
	s_waitcnt lgkmcnt(0)
	v_pk_mul_f32 v[158:159], v[92:93], v[100:101]
	v_pk_fma_f32 v[118:119], v[94:95], v[104:105], v[122:123] op_sel:[0,0,1] op_sel_hi:[1,1,0]
	v_pk_fma_f32 v[120:121], v[96:97], v[98:99], v[154:155] op_sel:[0,0,1] op_sel_hi:[1,1,0]
	v_pk_fma_f32 v[116:117], v[92:93], v[100:101], v[158:159] op_sel:[0,0,1] op_sel_hi:[1,1,0]
	ds_read_b128 v[98:101], v148 offset:384
	ds_read_b128 v[94:97], v148 offset:400
	s_waitcnt vmcnt(8)
	v_mov_b32_e32 v102, v192
	v_mov_b32_e32 v103, v193
	v_mov_b32_e32 v104, v194
	v_mov_b32_e32 v105, v195
	v_pk_mul_f32 v[156:157], v[90:91], v[114:115]
	v_cvt_pk_bf16_f32 v93, v158, v159
	v_pk_fma_f32 v[114:115], v[90:91], v[114:115], v[156:157] op_sel:[0,0,1] op_sel_hi:[1,1,0]
	v_cvt_pk_bf16_f32 v90, v122, v123
	v_cvt_pk_bf16_f32 v91, v154, v155
	v_cvt_pk_bf16_f32 v92, v156, v157
	s_waitcnt vmcnt(8)
	v_lshlrev_b32_e32 v122, 16, v102
	v_and_b32_e32 v123, 0xffff0000, v102
	v_lshlrev_b32_e32 v102, 16, v103
	v_and_b32_e32 v103, 0xffff0000, v103
	s_waitcnt lgkmcnt(1)
	v_pk_mul_f32 v[98:99], v[98:99], v[122:123]
	v_pk_mul_f32 v[122:123], v[100:101], v[102:103]
	v_lshlrev_b32_e32 v100, 16, v104
	v_and_b32_e32 v101, 0xffff0000, v104
	s_waitcnt lgkmcnt(0)
	v_pk_mul_f32 v[102:103], v[94:95], v[100:101]
	v_lshlrev_b32_e32 v94, 16, v105
	v_and_b32_e32 v95, 0xffff0000, v105
	v_pk_mul_f32 v[100:101], v[96:97], v[94:95]
	v_cvt_pk_bf16_f32 v94, v98, v99
	v_cvt_pk_bf16_f32 v95, v122, v123
	v_cvt_pk_bf16_f32 v96, v102, v103
	v_cvt_pk_bf16_f32 v97, v100, v101
	ds_read_b128 v[154:157], v149
	s_waitcnt lgkmcnt(0)
	v_mfma_f32_16x16x32_bf16 v[78:81], v[154:157], v[82:85], v[78:81]
	ds_read_b128 v[154:157], v149 offset:4352
	s_waitcnt lgkmcnt(0)
	v_mfma_f32_16x16x32_bf16 v[154:157], v[154:157], v[82:85], v[74:77]
	s_nop 2
	ds_read_b128 v[74:77], v149 offset:64
	s_waitcnt lgkmcnt(0)
	v_mfma_f32_16x16x32_bf16 v[74:77], v[74:77], v[86:89], v[78:81]
	s_nop 2
	ds_read_b128 v[78:81], v149 offset:128
	s_waitcnt lgkmcnt(0)
	v_mfma_f32_16x16x32_bf16 v[74:77], v[78:81], v[90:93], v[74:77]
	ds_read_b128 v[78:81], v149 offset:192
	s_waitcnt lgkmcnt(0)
	v_mfma_f32_16x16x32_bf16 v[74:77], v[78:81], v[94:97], v[74:77]
	ds_read_b128 v[78:81], v149 offset:4416
	s_waitcnt lgkmcnt(0)
	v_mfma_f32_16x16x32_bf16 v[78:81], v[78:81], v[86:89], v[154:157]
	s_nop 2
	ds_read_b128 v[154:157], v149 offset:4480
	s_waitcnt lgkmcnt(0)
	v_mfma_f32_16x16x32_bf16 v[78:81], v[154:157], v[90:93], v[78:81]
	ds_read_b128 v[154:157], v149 offset:4544
	s_waitcnt lgkmcnt(0)
	v_mfma_f32_16x16x32_bf16 v[78:81], v[154:157], v[94:97], v[78:81]
	ds_read_b128 v[154:157], v149 offset:8704
	s_waitcnt lgkmcnt(0)
	v_mfma_f32_16x16x32_bf16 v[70:73], v[154:157], v[82:85], v[70:73]
	ds_read_b128 v[154:157], v149 offset:8768
	s_waitcnt lgkmcnt(0)
	v_mfma_f32_16x16x32_bf16 v[70:73], v[154:157], v[86:89], v[70:73]
	ds_read_b128 v[154:157], v149 offset:8832
	s_waitcnt lgkmcnt(0)
	v_mfma_f32_16x16x32_bf16 v[70:73], v[154:157], v[90:93], v[70:73]
	ds_read_b128 v[154:157], v149 offset:8896
	s_waitcnt lgkmcnt(0)
	v_mfma_f32_16x16x32_bf16 v[70:73], v[154:157], v[94:97], v[70:73]
	ds_read_b128 v[154:157], v149 offset:13056
	s_waitcnt lgkmcnt(0)
	v_mfma_f32_16x16x32_bf16 v[66:69], v[154:157], v[82:85], v[66:69]
	ds_read_b128 v[154:157], v149 offset:13120
	s_waitcnt lgkmcnt(0)
	v_mfma_f32_16x16x32_bf16 v[66:69], v[154:157], v[86:89], v[66:69]
	ds_read_b128 v[154:157], v149 offset:13184
	s_waitcnt lgkmcnt(0)
	v_mfma_f32_16x16x32_bf16 v[66:69], v[154:157], v[90:93], v[66:69]
	ds_read_b128 v[154:157], v149 offset:13248
	s_waitcnt lgkmcnt(0)
	v_mfma_f32_16x16x32_bf16 v[66:69], v[154:157], v[94:97], v[66:69]
	ds_read_b128 v[154:157], v149 offset:17408
	v_mov_b32_e32 v119, v102
	v_mov_b32_e32 v121, v103
	v_mov_b32_e32 v115, v100
	v_mov_b32_e32 v117, v101
	v_mov_b32_e32 v111, v122
	v_mov_b32_e32 v113, v123
	v_mov_b32_e32 v109, v98
	v_mov_b32_e32 v98, v1
	s_waitcnt lgkmcnt(0)
	v_mfma_f32_16x16x32_bf16 v[62:65], v[154:157], v[82:85], v[62:65]
	ds_read_b128 v[154:157], v149 offset:17472
	s_waitcnt lgkmcnt(0)
	v_mfma_f32_16x16x32_bf16 v[62:65], v[154:157], v[86:89], v[62:65]
	ds_read_b128 v[154:157], v149 offset:17536
	s_waitcnt lgkmcnt(0)
	v_mfma_f32_16x16x32_bf16 v[62:65], v[154:157], v[90:93], v[62:65]
	ds_read_b128 v[154:157], v149 offset:17600
	s_waitcnt lgkmcnt(0)
	v_mfma_f32_16x16x32_bf16 v[62:65], v[154:157], v[94:97], v[62:65]
	ds_read_b128 v[154:157], v149 offset:21952
	ds_read_b128 v[158:161], v149 offset:21888
	ds_read_b128 v[162:165], v149 offset:21824
	ds_read_b128 v[170:173], v149 offset:21760
	s_waitcnt lgkmcnt(0)
	v_mfma_f32_16x16x32_bf16 v[58:61], v[170:173], v[82:85], v[58:61]
	v_mfma_f32_16x16x32_bf16 v[58:61], v[162:165], v[86:89], v[58:61]
	v_mfma_f32_16x16x32_bf16 v[58:61], v[158:161], v[90:93], v[58:61]
	v_mfma_f32_16x16x32_bf16 v[58:61], v[154:157], v[94:97], v[58:61]
	ds_read_b128 v[154:157], v149 offset:26304
	ds_read_b128 v[158:161], v149 offset:26240
	ds_read_b128 v[162:165], v149 offset:26176
	ds_read_b128 v[170:173], v149 offset:26112
	s_waitcnt lgkmcnt(0)
	v_mfma_f32_16x16x32_bf16 v[54:57], v[170:173], v[82:85], v[54:57]
	v_mfma_f32_16x16x32_bf16 v[54:57], v[162:165], v[86:89], v[54:57]
	v_mfma_f32_16x16x32_bf16 v[54:57], v[158:161], v[90:93], v[54:57]
	v_mfma_f32_16x16x32_bf16 v[54:57], v[154:157], v[94:97], v[54:57]
	ds_read_b128 v[154:157], v149 offset:30656
	ds_read_b128 v[158:161], v149 offset:30592
	ds_read_b128 v[162:165], v149 offset:30528
	ds_read_b128 v[170:173], v149 offset:30464
	s_waitcnt lgkmcnt(0)
	v_mfma_f32_16x16x32_bf16 v[50:53], v[170:173], v[82:85], v[50:53]
	v_add_f32_e64 v84, v118, v120
	v_add_f32_e64 v85, v119, v121
	v_pk_add_f32 v[82:83], v[110:111], v[112:113]
	v_mfma_f32_16x16x32_bf16 v[50:53], v[162:165], v[86:89], v[50:53]
	v_add_f32_e64 v86, v114, v116
	v_add_f32_e64 v87, v115, v117
	v_pk_add_f32 v[84:85], v[84:85], v[86:87]
	v_mfma_f32_16x16x32_bf16 v[50:53], v[158:161], v[90:93], v[50:53]
	v_add_f32_e64 v86, v108, v98
	v_add_f32_e64 v87, v109, v99
	v_pk_add_f32 v[82:83], v[86:87], v[82:83]
	v_mfma_f32_16x16x32_bf16 v[50:53], v[154:157], v[94:97], v[50:53]
	v_add_f32_e64 v82, v82, v84
	v_add_f32_e64 v83, v83, v85
	v_add_f32_e32 v82, v82, v83
	ds_bpermute_b32 v83, v145, v82
	s_add_i32 s81, s81, -1
	s_mov_b64 s[60:61], 0
	s_waitcnt lgkmcnt(0)
	v_add_f32_e32 v82, v82, v83
	ds_bpermute_b32 v83, v146, v82
	s_waitcnt lgkmcnt(0)
	v_add_f32_e32 v82, v82, v83
	v_fmac_f32_e32 v82, v152, v0

.LBB0_287:
	s_cmp_lg_u32 s97, 0
	s_cselect_b64 s[52:53], -1, 0
	s_cmp_lt_u32 s97, s80
	s_cselect_b64 s[60:61], -1, 0
	s_and_b64 s[52:53], s[52:53], s[60:61]
	s_or_b64 s[52:53], s[40:41], s[52:53]
	s_waitcnt vmcnt(8)
	v_mov_b32_e32 v5, v53
	v_mov_b32_e32 v4, v52
	v_mov_b32_e32 v3, v51
	v_mov_b32_e32 v2, v50
	v_mov_b32_e32 v9, v57
	v_mov_b32_e32 v8, v56
	v_mov_b32_e32 v7, v55
	v_mov_b32_e32 v6, v54
	v_mov_b32_e32 v13, v61
	v_mov_b32_e32 v12, v60
	v_mov_b32_e32 v11, v59
	v_mov_b32_e32 v10, v58
	v_mov_b32_e32 v17, v65
	v_mov_b32_e32 v16, v64
	v_mov_b32_e32 v15, v63
	v_mov_b32_e32 v14, v62
	v_mov_b32_e32 v29, v69
	v_mov_b32_e32 v28, v68
	v_mov_b32_e32 v27, v67
	v_mov_b32_e32 v26, v66
	v_mov_b32_e32 v33, v73
	v_mov_b32_e32 v32, v72
	v_mov_b32_e32 v31, v71
	v_mov_b32_e32 v30, v70
	v_mov_b32_e32 v45, v81
	v_mov_b32_e32 v44, v80
	v_mov_b32_e32 v43, v79
	v_mov_b32_e32 v42, v78
	v_mov_b32_e32 v49, v77
	v_mov_b32_e32 v48, v76
	v_mov_b32_e32 v47, v75
	v_mov_b32_e32 v46, v74
	v_mov_b32_e32 v151, v153
	s_andn2_b64 vcc, exec, s[52:53]
	v_mov_b32_e32 v152, v82
	s_cbranch_vccnz .LBB0_293
	s_add_i32 s60, s95, s97
	s_and_b64 s[52:53], s[40:41], exec
	s_cselect_b32 s52, s60, s85
	s_ashr_i32 s53, s52, 31
	s_lshl_b64 s[60:61], s[52:53], 17
	s_mul_hi_i32 s96, s52, 0x440
	s_mul_i32 vcc_lo, s52, 0x440
	s_add_u32 s52, s3, s60
	v_mov_b32_e32 v0, v127
	s_addc_u32 s53, s92, s61
	v_cvt_pk_bf16_f32 v52, v46, s0
	global_store_short v0, v52, s[52:53]
	v_cvt_pk_bf16_f32 v52, v47, s0
	global_store_short v0, v52, s[52:53] offset:512
	v_cvt_pk_bf16_f32 v52, v48, s0
	global_store_short v0, v52, s[52:53] offset:1024
	v_cvt_pk_bf16_f32 v52, v49, s0
	v_lshl_add_u64 v[50:51], s[52:53], 0, v[0:1]
	global_store_short v0, v52, s[52:53] offset:1536
	s_mov_b64 s[52:53], 0x2000
	v_lshl_add_u64 v[50:51], v[50:51], 0, s[52:53]
	v_cvt_pk_bf16_f32 v0, v42, s0
	global_store_short v[50:51], v0, off
	v_cvt_pk_bf16_f32 v0, v43, s0
	global_store_short v[50:51], v0, off offset:512
	v_cvt_pk_bf16_f32 v0, v44, s0
	global_store_short v[50:51], v0, off offset:1024
	v_cvt_pk_bf16_f32 v0, v45, s0
	global_store_short v[50:51], v0, off offset:1536
	v_lshl_add_u64 v[50:51], v[50:51], 0, s[52:53]
	v_cvt_pk_bf16_f32 v0, v30, s0
	global_store_short v[50:51], v0, off
	v_cvt_pk_bf16_f32 v0, v31, s0
	global_store_short v[50:51], v0, off offset:512
	v_cvt_pk_bf16_f32 v0, v32, s0
	global_store_short v[50:51], v0, off offset:1024
	v_cvt_pk_bf16_f32 v0, v33, s0
	global_store_short v[50:51], v0, off offset:1536
	v_lshl_add_u64 v[50:51], v[50:51], 0, s[52:53]
	v_cvt_pk_bf16_f32 v0, v26, s0
	global_store_short v[50:51], v0, off
	v_cvt_pk_bf16_f32 v0, v27, s0
	global_store_short v[50:51], v0, off offset:512
	v_cvt_pk_bf16_f32 v0, v28, s0
	global_store_short v[50:51], v0, off offset:1024
	v_cvt_pk_bf16_f32 v0, v29, s0
	global_store_short v[50:51], v0, off offset:1536
	v_lshl_add_u64 v[50:51], v[50:51], 0, s[52:53]
	v_cvt_pk_bf16_f32 v0, v14, s0
	global_store_short v[50:51], v0, off
	v_cvt_pk_bf16_f32 v0, v15, s0
	global_store_short v[50:51], v0, off offset:512
	v_cvt_pk_bf16_f32 v0, v16, s0
	global_store_short v[50:51], v0, off offset:1024
	v_cvt_pk_bf16_f32 v0, v17, s0
	global_store_short v[50:51], v0, off offset:1536
	v_lshl_add_u64 v[50:51], v[50:51], 0, s[52:53]
	v_cvt_pk_bf16_f32 v0, v10, s0
	global_store_short v[50:51], v0, off
	v_cvt_pk_bf16_f32 v0, v11, s0
	global_store_short v[50:51], v0, off offset:512
	v_cvt_pk_bf16_f32 v0, v12, s0
	global_store_short v[50:51], v0, off offset:1024
	v_cvt_pk_bf16_f32 v0, v13, s0
	global_store_short v[50:51], v0, off offset:1536
	v_lshl_add_u64 v[50:51], v[50:51], 0, s[52:53]
	v_cvt_pk_bf16_f32 v0, v6, s0
	global_store_short v[50:51], v0, off
	v_cvt_pk_bf16_f32 v0, v7, s0
	global_store_short v[50:51], v0, off offset:512
	v_cvt_pk_bf16_f32 v0, v8, s0
	global_store_short v[50:51], v0, off offset:1024
	v_cvt_pk_bf16_f32 v0, v9, s0
	global_store_short v[50:51], v0, off offset:1536
	v_lshl_add_u64 v[50:51], v[50:51], 0, s[52:53]
	v_cvt_pk_bf16_f32 v0, v2, s0
	global_store_short v[50:51], v0, off
	v_cvt_pk_bf16_f32 v0, v3, s0
	global_store_short v[50:51], v0, off offset:512
	v_cvt_pk_bf16_f32 v0, v4, s0
	global_store_short v[50:51], v0, off offset:1024
	v_cvt_pk_bf16_f32 v0, v5, s0
	s_add_u32 s60, s66, vcc_lo
	global_store_short v[50:51], v0, off offset:1536
	v_lshl_add_u64 v[50:51], v[50:51], 0, s[52:53]
	s_addc_u32 s61, s67, s96
	s_and_saveexec_b64 s[52:53], s[56:57]
	s_cbranch_execz .LBB0_290
	v_lshl_add_u64 v[50:51], v[106:107], 2, s[60:61]
	global_store_dword v[50:51], v152, off

.LBB0_293:
	s_cmp_eq_u32 s62, s97
	s_mov_b64 s[60:61], -1
	s_cbranch_scc1 .LBB0_286
	v_mov_b32_e32 v52, v124
	s_barrier
	s_movk_i32 s60, 0x110
	v_lshlrev_b32_e32 v0, 4, v52
	v_and_b32_e32 v0, 0xf0, v0
	v_add_u32_e32 v0, 0, v0
	v_lshrrev_b32_e32 v50, 4, v52
	v_mad_u64_u32 v[50:51], s[52:53], v50, s60, v[0:1]
	s_waitcnt vmcnt(7)
	ds_write_b128 v50, v[18:21]
	v_add_u32_e32 v50, 0x200, v52
	v_lshrrev_b32_e32 v50, 4, v50
	v_mad_u64_u32 v[50:51], s[52:53], v50, s60, v[0:1]
	s_waitcnt vmcnt(6)
	ds_write_b128 v50, v[22:25]
	v_add_u32_e32 v50, 0x400, v52
	v_lshrrev_b32_e32 v50, 4, v50
	v_mad_u64_u32 v[50:51], s[52:53], v50, s60, v[0:1]
	s_waitcnt vmcnt(5)
	ds_write_b128 v50, v[34:37]
	v_add_u32_e32 v50, 0x600, v52
	v_lshrrev_b32_e32 v50, 4, v50
	s_add_i32 s96, s97, 1
	v_mad_u64_u32 v[50:51], s[52:53], v50, s60, v[0:1]
	s_cmp_ge_u32 s96, s62
	s_waitcnt vmcnt(4)
	ds_write_b128 v50, v[38:41]
	s_waitcnt lgkmcnt(0)
	s_barrier
	s_and_b64 s[52:53], s[50:51], exec
	s_cselect_b32 s52, s97, s81
	s_lshl_b32 s52, s52, 7
	s_add_i32 s60, s52, s44
	v_add_u32_e32 v50, s60, v128
	v_ashrrev_i32_e32 v51, 31, v50
	v_lshlrev_b64 v[50:51], 6, v[50:51]
	v_mov_b32_e32 v102, v126
	v_lshl_add_u64 v[54:55], s[58:59], 0, v[50:51]
	s_cmp_lg_u32 s97, 0
	s_cbranch_scc1 .Lml1g_pref
	global_load_dword v53, v[54:55], off offset:80
	global_load_dword v51, v[54:55], off offset:16
	global_load_dword v0, v[54:55], off offset:64
	global_load_dword v50, v[54:55], off
	s_branch .Lml1g_go
.Lml1g_pref:
	s_waitcnt vmcnt(0)
	v_mov_b32_e32 v53, v196
	v_mov_b32_e32 v51, v197
	v_mov_b32_e32 v0, v198
	v_mov_b32_e32 v50, v199
.Lml1g_go:
	s_mov_b32 s100, s60
	s_ashr_i32 s101, s60, 31
	s_lshl_b64 s[100:101], s[100:101], 1
	s_add_u32 s100, s93, s100
	s_addc_u32 s101, s94, s101
	global_load_dwordx4 v[180:183], v102, s[100:101]
	global_load_dwordx4 v[184:187], v102, s[100:101] offset:64
	global_load_dwordx4 v[188:191], v102, s[100:101] offset:128
	global_load_dwordx4 v[192:195], v102, s[100:101] offset:192
	s_cmp_ge_u32 s96, s62
	s_cbranch_scc1 .Lml1a_nopre
	v_mov_b32_e32 v175, 0
	s_add_i32 s100, s81, -1
	s_and_b64 s[52:53], s[50:51], exec
	s_cselect_b32 s52, s96, s100
	s_lshl_b32 s52, s52, 7
	s_add_i32 s61, s52, s44
	s_ashr_i32 s53, s52, 31
	v_mov_b32_e32 v38, v124
	s_lshl_b64 s[52:53], s[52:53], 1
	s_add_u32 s52, s45, s52
	v_lshlrev_b32_e32 v174, 4, v38
	s_addc_u32 s53, s84, s53
	v_and_b32_e32 v174, 0xf0, v174
	v_lshl_add_u64 v[34:35], s[52:53], 0, v[174:175]
	v_ashrrev_i32_e32 v174, 4, v38
	s_movk_i32 s100, 0x6000
	v_mad_i64_i32 v[18:19], s[52:53], v174, s100, v[34:35]
	v_add_u32_e32 v174, 0x200, v38
	v_ashrrev_i32_e32 v174, 4, v174
	v_mad_i64_i32 v[22:23], s[52:53], v174, s100, v[34:35]
	v_add_u32_e32 v174, 0x400, v38
	v_ashrrev_i32_e32 v174, 4, v174
	v_mad_i64_i32 v[36:37], s[52:53], v174, s100, v[34:35]
	v_add_u32_e32 v174, 0x600, v38
	v_ashrrev_i32_e32 v174, 4, v174
	v_mad_i64_i32 v[38:39], s[52:53], v174, s100, v[34:35]
	global_load_dwordx4 v[18:21], v[18:19], off
	s_nop 0
	global_load_dwordx4 v[22:25], v[22:23], off
	s_nop 0
	global_load_dwordx4 v[34:37], v[36:37], off
	s_nop 0
	global_load_dwordx4 v[38:41], v[38:39], off
	v_add_u32_e32 v200, s61, v128
	v_ashrrev_i32_e32 v201, 31, v200
	v_lshlrev_b64 v[200:201], 6, v[200:201]
	v_lshl_add_u64 v[200:201], s[58:59], 0, v[200:201]
	global_load_dword v196, v[200:201], off offset:80
	global_load_dword v197, v[200:201], off offset:16
	global_load_dword v198, v[200:201], off offset:64
	global_load_dword v199, v[200:201], off
	s_branch .Lml1a_join
.Lml1a_nopre:
	global_load_dword v176, v[54:55], off
	global_load_dword v176, v[54:55], off
	global_load_dword v176, v[54:55], off
	global_load_dword v176, v[54:55], off
	global_load_dword v176, v[54:55], off
	global_load_dword v176, v[54:55], off
	global_load_dword v176, v[54:55], off
	global_load_dword v176, v[54:55], off
.Lml1a_join:
	s_andn2_b64 vcc, exec, s[48:49]
	s_mov_b64 s[52:53], -1
	s_waitcnt vmcnt(14)
	v_add_f32_e32 v52, v51, v53
	s_cbranch_vccnz .LBB0_298
	ds_bpermute_b32 v54, v129, v52
	s_mov_b64 s[52:53], 0
	s_waitcnt lgkmcnt(0)
	v_add_f32_e32 v54, v52, v54
	v_cndmask_b32_e64 v54, v52, v54, s[8:9]
	ds_bpermute_b32 v55, v130, v54
	s_waitcnt lgkmcnt(0)
	v_add_f32_e32 v55, v54, v55
	v_cndmask_b32_e64 v54, v54, v55, s[10:11]
	ds_bpermute_b32 v55, v131, v54
	s_waitcnt lgkmcnt(0)
	v_add_f32_e32 v55, v54, v55
	v_cndmask_b32_e64 v54, v54, v55, s[12:13]
	ds_bpermute_b32 v55, v132, v54
	s_waitcnt lgkmcnt(0)
	v_add_f32_e32 v55, v54, v55
	v_cndmask_b32_e64 v54, v54, v55, s[14:15]
	ds_bpermute_b32 v55, v133, v54
	s_waitcnt lgkmcnt(0)
	v_add_f32_e32 v55, v54, v55
	v_cndmask_b32_e64 v54, v54, v55, s[16:17]
	ds_bpermute_b32 v55, v134, v54
	s_waitcnt lgkmcnt(0)
	v_add_f32_e32 v55, v54, v55
	v_cndmask_b32_e64 v54, v54, v55, s[18:19]
	ds_bpermute_b32 v55, v129, v54
	v_readlane_b32 s61, v54, 0
	s_waitcnt lgkmcnt(0)
	v_cndmask_b32_e64 v55, v55, 0, s[20:21]
	v_add_f32_e32 v55, v53, v55
